# ret_out-32-short-stores-per-lane-replaced-by-LDS-transpose-plus-4-dwordx4-stores
# baseline (speedup 1.0000x reference)
; #define LAS __attribute__((address_space(3)))
; __device__ __forceinline__ float ret_log2g(int h) { const float e = exp2f(-5.0f - (float)h); return -1.4426950408889634f * (e + e * e * (0.5f + e * (0.33333333f + e * 0.25f))); }
; __device__ __forceinline__ void stage_vt(const bf16* rawB, int b, int h, int j, LAS bf16* Vt, int tid) {
;     const int m = tid >> 2, part = tid & 3;
;     const bf16* src = rawB + ((size_t)b * SEQ + j * RC + m) * 2048 + 1024 + h * 128 + 32 * part;
; #pragma unroll
;     for (int q = 0; q < 4; ++q) { float f[8]; const u32x4 u = *(const u32x4*)(src + 8 * q);
;         const unsigned w[4] = {u.x, u.y, u.z, u.w};
; #pragma unroll
;         for (int i = 0; i < 4; ++i) { Vt[(32 * part + 8 * q + 2 * i) * KP + m] = (bf16)(w[i] & 0xffffu); Vt[(32 * part + 8 * q + 2 * i + 1) * KP + m] = (bf16)(w[i] >> 16); }
;         (void)f; }
; }
; __device__ __forceinline__ void rot8(const bf16* src, const float* rot, int pos, int part, float scale, float* o1, float* o2) {
;     float x1[8], x2[8]; unpack8(*(const u32x4*)(src + 8 * part), x1); unpack8(*(const u32x4*)(src + 32 + 8 * part), x2);
;     const float* cs = rot + (size_t)pos * 32 + 8 * part; const float* sn = rot + (size_t)2048 * 32 + (size_t)pos * 32 + 8 * part;
; __device__ __forceinline__ void ret_out_phase(int l, LAS unsigned char* lds, int wave, int lane_) {
;     ...
;     for (int it = blockIdx.x; it < BATCH * 8 * NRC; it += gridDim.x) {
;         const int j = it % NRC, bh = it / NRC, b = bh >> 3, h = bh & 7;
;         const float l2g = ret_log2g(h);
;         const __amdgpu_buffer_rsrc_t strs = __builtin_amdgcn_make_buffer_rsrc((void*)(ws + OFF_ST), 0, 0x7fffffff, 0x00027000);
;         const unsigned sfo = (unsigned)(((bh * NRC + j) * 2 + 0) * 8192 * 2);
;         u32x4 sfv[4][2], sbv[4][2];
;     ...
;         RET_LD_STATES(0);
;         {
;             const int m = tid >> 2, part = tid & 3; const int pos = j * RC + m;
;             const bf16* src = rawB + ((size_t)b * SEQ + pos) * 2048 + h * 64;
;             float o1[8], o2[8];
;             rot8(src, rot, pos, part, 0.125f, o1, o2);
;             *(LAS u32x4*)(Qs + m * QP + 8 * part) = pack8u(o1); *(LAS u32x4*)(Qs + m * QP + 32 + 8 * part) = pack8u(o2);
;             rot8(src + 512, rot, pos, part, 1.0f, o1, o2);
;             *(LAS u32x4*)(Ks + m * QP + 8 * part) = pack8u(o1); *(LAS u32x4*)(Ks + m * QP + 32 + 8 * part) = pack8u(o2);
.LBB0_632:
	s_ashr_i32 s34, s46, 31
	s_lshr_b32 s34, s34, 28
	s_add_i32 s36, s46, s34
	s_ashr_i32 s37, s36, 4
	s_and_b32 s42, s37, 7
	v_cvt_f32_ubyte0_e32 v4, s42
	v_sub_f32_e32 v4, 0xc0a00000, v4
	v_cmp_gt_f32_e32 vcc, s50, v4
	s_and_b64 s[34:35], vcc, exec
	s_cselect_b32 s34, 0xffffffc0, 0
	v_cndmask_b32_e32 v5, 0, v206, vcc
	v_add_f32_e32 v4, v4, v5
	v_exp_f32_e32 v4, v4
	s_lshl_b32 s35, s37, 11
	v_ldexp_f32 v76, v4, s34
	s_ashr_i32 s34, s36, 7
	s_sub_i32 s36, s29, s35
	v_add_u32_e32 v78, s36, v94
	s_ashr_i32 s35, s34, 31
	s_lshl_b64 s[34:35], s[34:35], 11
	v_ashrrev_i32_e32 v79, 31, v78
	v_lshl_add_u64 v[68:69], s[34:35], 0, v[78:79]
	v_fmamk_f32 v77, v76, 0x3e800000, v201
	v_lshlrev_b64 v[68:69], 12, v[68:69]
	v_pk_mul_f32 v[4:5], v[76:77], v[76:77] op_sel_hi:[0,1]
	v_lshl_add_u64 v[68:69], s[44:45], 0, v[68:69]
	s_lshl_b32 s96, s42, 7
	v_add_f32_e32 v5, 0.5, v5
	v_lshl_add_u64 v[68:69], v[68:69], 0, s[96:97]
	v_fmac_f32_e32 v76, v4, v5
	v_lshl_add_u64 v[90:91], v[68:69], 0, v[2:3]
	v_lshlrev_b64 v[78:79], 7, v[78:79]
	v_lshl_add_u64 v[82:83], v[96:97], 0, v[78:79]
	v_lshl_add_u64 v[110:111], v[98:99], 0, v[78:79]
	s_ashr_i32 s37, s36, 31
	s_add_u32 s34, s34, s36
	s_addc_u32 s35, s35, s37
	s_nop 0
	global_load_dwordx4 v[68:71], v[90:91], off
	global_load_dwordx4 v[72:75], v[90:91], off offset:64
	global_load_dwordx4 v[78:81], v[82:83], off offset:16
	s_nop 0
	global_load_dwordx4 v[82:85], v[82:83], off
	s_nop 0
	global_load_dwordx4 v[86:89], v[110:111], off offset:16
	s_nop 0
	global_load_dwordx4 v[110:113], v[110:111], off
	s_lshl_b32 s96, s42, 8
	v_mov_b32_e32 v109, v3
	s_add_u32 s36, s6, s96
	s_addc_u32 s37, s7, 0
	global_load_dwordx4 v[224:227], v[90:91], off offset:1024
	global_load_dwordx4 v[228:231], v[90:91], off offset:1088
	v_lshl_add_u64 v[248:249], s[34:35], 0, v[94:95]
	v_lshlrev_b64 v[248:249], 12, v[248:249]
	v_lshl_add_u64 v[248:249], s[44:45], 0, v[248:249]
	v_lshl_add_u64 v[248:249], v[248:249], 0, s[96:97]
	v_lshl_add_u64 v[248:249], v[248:249], 0, v[108:109]
	global_load_dwordx4 v[232:235], v[248:249], off offset:2048
	global_load_dwordx4 v[236:239], v[248:249], off offset:2064
	global_load_dwordx4 v[240:243], v[248:249], off offset:2080
	global_load_dwordx4 v[244:247], v[248:249], off offset:2096
	v_add_u32_e32 v12, 0xffff8800, v161
	s_waitcnt vmcnt(17)
	v_add_u32_e32 v20, 0xffffcfc0, v161
	buffer_load_dwordx4 v[16:19], v12, s[60:63], 0 offen sc0 sc1
	s_waitcnt vmcnt(16)
	v_add_u32_e32 v28, 0xffff9000, v161
	buffer_load_dwordx4 v[20:23], v20, s[60:63], 0 offen sc0 sc1
	v_add_u32_e32 v12, 0xffffc800, v161
	v_add_u32_e32 v44, 0xffff9800, v161
	v_add_u32_e32 v52, 0xffffdfc0, v161
	buffer_load_dwordx4 v[24:27], v12, s[60:63], 0 offen sc0 sc1
	buffer_load_dwordx4 v[32:35], v28, s[60:63], 0 offen sc0 sc1
	v_add_u32_e32 v12, 0xffff8fc0, v161
	v_add_u32_e32 v28, 0xffffd000, v161
	buffer_load_dwordx4 v[48:51], v44, s[60:63], 0 offen sc0 sc1
	v_add_u32_e32 v60, 0xffffa000, v161
	buffer_load_dwordx4 v[52:55], v52, s[60:63], 0 offen sc0 sc1
	v_add_u32_e32 v44, 0xffffd800, v161
	v_add_u32_e32 v4, 0xffff87c0, v161
	v_add_u32_e32 v8, 0xffffc7c0, v161
	buffer_load_dwordx4 v[12:15], v12, s[60:63], 0 offen sc0 sc1
	s_waitcnt vmcnt(20)
	v_add_u32_e32 v36, 0xffffd7c0, v161
	buffer_load_dwordx4 v[40:43], v28, s[60:63], 0 offen sc0 sc1
	v_add_u32_e32 v28, 0xffff97c0, v161
	buffer_load_dwordx4 v[56:59], v44, s[60:63], 0 offen sc0 sc1
	v_add_u32_e32 v64, 0xffffe000, v161
	buffer_load_dwordx4 v[60:63], v60, s[60:63], 0 offen sc0 sc1
	v_add_u32_e32 v44, 0xffff9fc0, v161
	buffer_load_dwordx4 v[4:7], v4, s[60:63], 0 offen sc0 sc1
	buffer_load_dwordx4 v[8:11], v8, s[60:63], 0 offen sc0 sc1
	buffer_load_dwordx4 v[28:31], v28, s[60:63], 0 offen sc0 sc1
	buffer_load_dwordx4 v[36:39], v36, s[60:63], 0 offen sc0 sc1
	buffer_load_dwordx4 v[44:47], v44, s[60:63], 0 offen sc0 sc1
	buffer_load_dwordx4 v[64:67], v64, s[60:63], 0 offen sc0 sc1
	s_waitcnt vmcnt(27)
	v_lshlrev_b32_e32 v114, 16, v68
	s_waitcnt vmcnt(26)
	v_lshlrev_b32_e32 v116, 16, v72
	v_and_b32_e32 v117, 0xffff0000, v72
	v_and_b32_e32 v115, 0xffff0000, v68
	s_waitcnt vmcnt(22)
	v_pk_mul_f32 v[182:183], v[110:111], v[116:117]
	v_lshlrev_b32_e32 v72, 16, v73
	v_pk_fma_f32 v[182:183], v[82:83], v[114:115], v[182:183] neg_lo:[0,0,1] neg_hi:[0,0,1]
	v_pk_mul_f32 v[114:115], v[110:111], v[114:115]
	v_and_b32_e32 v73, 0xffff0000, v73
	v_pk_fma_f32 v[114:115], v[82:83], v[116:117], v[114:115]
	v_lshlrev_b32_e32 v68, 16, v69
	v_and_b32_e32 v69, 0xffff0000, v69
	v_pk_mul_f32 v[116:117], v[112:113], v[72:73]
	v_lshlrev_b32_e32 v184, 16, v74
	v_pk_fma_f32 v[116:117], v[84:85], v[68:69], v[116:117] neg_lo:[0,0,1] neg_hi:[0,0,1]
	v_pk_mul_f32 v[68:69], v[112:113], v[68:69]
	v_and_b32_e32 v185, 0xffff0000, v74
	v_pk_fma_f32 v[68:69], v[84:85], v[72:73], v[68:69]
	v_pk_mul_f32 v[186:187], v[86:87], v[184:185]
	v_pk_mul_f32 v[72:73], v[68:69], s[88:89] op_sel_hi:[1,0]
	v_lshlrev_b32_e32 v68, 16, v70
	v_and_b32_e32 v69, 0xffff0000, v70
	v_pk_fma_f32 v[186:187], v[78:79], v[68:69], v[186:187] neg_lo:[0,0,1] neg_hi:[0,0,1]
	v_pk_mul_f32 v[68:69], v[86:87], v[68:69]
	v_lshlrev_b32_e32 v70, 16, v75
	v_pk_fma_f32 v[68:69], v[78:79], v[184:185], v[68:69]
	v_pk_mul_f32 v[182:183], v[182:183], s[88:89] op_sel_hi:[1,0]
	v_pk_mul_f32 v[184:185], v[68:69], s[88:89] op_sel_hi:[1,0]
	v_lshlrev_b32_e32 v68, 16, v71
	v_and_b32_e32 v69, 0xffff0000, v71
	v_and_b32_e32 v71, 0xffff0000, v75
	v_pk_mul_f32 v[74:75], v[88:89], v[70:71]
	v_pk_mul_f32 v[116:117], v[116:117], s[88:89] op_sel_hi:[1,0]
	v_pk_fma_f32 v[74:75], v[80:81], v[68:69], v[74:75] neg_lo:[0,0,1] neg_hi:[0,0,1]
	v_pk_mul_f32 v[68:69], v[88:89], v[68:69]
	v_pk_mul_f32 v[186:187], v[186:187], s[88:89] op_sel_hi:[1,0]
	v_pk_mul_f32 v[74:75], v[74:75], s[88:89] op_sel_hi:[1,0]
	v_pk_fma_f32 v[68:69], v[80:81], v[70:71], v[68:69]
	v_pk_mul_f32 v[114:115], v[114:115], s[88:89] op_sel_hi:[1,0]
	v_pk_mul_f32 v[188:189], v[68:69], s[88:89] op_sel_hi:[1,0]
	v_cvt_pk_bf16_f32 v68, v182, v183
	v_cvt_pk_bf16_f32 v69, v116, v117
	v_cvt_pk_bf16_f32 v70, v186, v187
	v_cvt_pk_bf16_f32 v71, v74, v75
	ds_write_b128 v118, v[68:71]
	v_cvt_pk_bf16_f32 v68, v114, v115
	v_cvt_pk_bf16_f32 v69, v72, v73
	v_cvt_pk_bf16_f32 v70, v184, v185
	v_cvt_pk_bf16_f32 v71, v188, v189
	ds_write_b128 v118, v[68:71] offset:64
	s_waitcnt vmcnt(21)
; #define LAS __attribute__((address_space(3)))
; #define LDS_WAIT() asm volatile("s_waitcnt lgkmcnt(0)" ::: "memory")
; __device__ __forceinline__ unsigned f2bf(float f) { return cvtpk(f, 0.f) & 0xffffu; }
; __device__ __forceinline__ u32x4 pack8u(const float* f) { u32x4 u; u.x = pk2(f[0], f[1]); u.y = pk2(f[2], f[3]); u.z = pk2(f[4], f[5]); u.w = pk2(f[6], f[7]); return u; }
; #define MFMA16(a, b, c) __builtin_amdgcn_mfma_f32_16x16x32_bf16((a), (b), (c), 0, 0, 0)
; __device__ __forceinline__ void stage_vt(const bf16* rawB, int b, int h, int j, LAS bf16* Vt, int tid) {
;     ...
;     for (int q = 0; q < 4; ++q) { float f[8]; const u32x4 u = *(const u32x4*)(src + 8 * q);
;         const unsigned w[4] = {u.x, u.y, u.z, u.w};
; #pragma unroll
;         for (int i = 0; i < 4; ++i) { Vt[(32 * part + 8 * q + 2 * i) * KP + m] = (bf16)(w[i] & 0xffffu); Vt[(32 * part + 8 * q + 2 * i + 1) * KP + m] = (bf16)(w[i] >> 16); }
; __device__ __forceinline__ void ret_out_phase(int l, LAS unsigned char* lds, int wave, int lane_) {
;     ...
;             rot8(src + 512, rot, pos, part, 1.0f, o1, o2);
;             *(LAS u32x4*)(Ks + m * QP + 8 * part) = pack8u(o1); *(LAS u32x4*)(Ks + m * QP + 32 + 8 * part) = pack8u(o2);
;             stage_vt(rawB, b, h, j, Vt, tid);
;         }
;         LDS_WAIT(); __syncthreads();
;         bf16x8 aq[2];
; #pragma unroll
;         for (int ks = 0; ks < 2; ++ks) aq[ks] = *(const LAS bf16x8*)(Qs + (16 * wave + fr) * QP + 32 * ks + 8 * fq);
; #pragma unroll
;         for (int nb = 0; nb < 8; ++nb) {
;             f32x4 sc = {0.f, 0.f, 0.f, 0.f};
; #pragma unroll
;             for (int ks = 0; ks < 2; ++ks) { const bf16x8 bk = *(const LAS bf16x8*)(Ks + (nb * 16 + fr) * QP + 32 * ks + 8 * fq); sc = MFMA16(aq[ks], bk, sc); }
; #pragma unroll
;             for (int i = 0; i < 4; ++i) { const int n = 16 * wave + 4 * fq + i, mk = nb * 16 + fr; const int d = n > mk ? n - mk : mk - n;
;                 Pw[(4 * fq + i) * KP + mk] = (bf16)f2bf(sc[i] * __builtin_amdgcn_exp2f(l2g * (float)d)); }
	v_lshlrev_b32_e32 v90, 16, v224
	s_waitcnt vmcnt(20)
	v_lshlrev_b32_e32 v114, 16, v228
	v_and_b32_e32 v115, 0xffff0000, v228
	v_and_b32_e32 v91, 0xffff0000, v224
	v_pk_mul_f32 v[116:117], v[110:111], v[114:115]
	v_lshlrev_b32_e32 v228, 16, v229
	v_pk_fma_f32 v[116:117], v[82:83], v[90:91], v[116:117] neg_lo:[0,0,1] neg_hi:[0,0,1]
	v_pk_mul_f32 v[82:83], v[82:83], v[114:115]
	v_and_b32_e32 v229, 0xffff0000, v229
	v_pk_fma_f32 v[82:83], v[110:111], v[90:91], v[82:83]
	v_lshlrev_b32_e32 v224, 16, v225
	v_and_b32_e32 v225, 0xffff0000, v225
	v_pk_mul_f32 v[90:91], v[112:113], v[228:229]
	v_pk_mul_f32 v[228:229], v[84:85], v[228:229]
	v_pk_fma_f32 v[90:91], v[84:85], v[224:225], v[90:91] neg_lo:[0,0,1] neg_hi:[0,0,1]
	v_lshlrev_b32_e32 v84, 16, v230
	v_and_b32_e32 v85, 0xffff0000, v230
	v_pk_fma_f32 v[228:229], v[112:113], v[224:225], v[228:229]
	v_lshlrev_b32_e32 v224, 16, v226
	v_and_b32_e32 v225, 0xffff0000, v226
	v_pk_mul_f32 v[110:111], v[86:87], v[84:85]
	v_lshlrev_b32_e32 v226, 16, v231
	v_pk_fma_f32 v[110:111], v[78:79], v[224:225], v[110:111] neg_lo:[0,0,1] neg_hi:[0,0,1]
	v_pk_mul_f32 v[78:79], v[78:79], v[84:85]
	v_mul_f32_e32 v84, 0xbfb8aa3b, v76
	v_pk_fma_f32 v[78:79], v[86:87], v[224:225], v[78:79]
	v_lshlrev_b32_e32 v224, 16, v227
	v_and_b32_e32 v225, 0xffff0000, v227
	v_and_b32_e32 v227, 0xffff0000, v231
	v_pk_mul_f32 v[230:231], v[88:89], v[226:227]
	v_pk_mul_f32 v[226:227], v[80:81], v[226:227]
	v_pk_fma_f32 v[230:231], v[80:81], v[224:225], v[230:231] neg_lo:[0,0,1] neg_hi:[0,0,1]
	v_pk_fma_f32 v[80:81], v[88:89], v[224:225], v[226:227]
	v_cvt_pk_bf16_f32 v224, v116, v117
	v_cvt_pk_bf16_f32 v225, v90, v91
	v_cvt_pk_bf16_f32 v226, v110, v111
	v_cvt_pk_bf16_f32 v227, v230, v231
	ds_write_b128 v118, v[224:227] offset:18432
	v_cvt_pk_bf16_f32 v224, v82, v83
	v_cvt_pk_bf16_f32 v225, v228, v229
	v_cvt_pk_bf16_f32 v226, v78, v79
	v_cvt_pk_bf16_f32 v227, v80, v81
	ds_write_b128 v118, v[224:227] offset:18496
	s_waitcnt vmcnt(19)
	ds_write_b16 v119, v232 offset:36864
	ds_write_b16_d16_hi v119, v232 offset:37136
	ds_write_b16 v119, v233 offset:37408
	ds_write_b16_d16_hi v119, v233 offset:37680
	ds_write_b16 v119, v234 offset:37952
	ds_write_b16_d16_hi v119, v234 offset:38224
	ds_write_b16 v119, v235 offset:38496
	ds_write_b16_d16_hi v119, v235 offset:38768
	s_waitcnt vmcnt(18)
	ds_write_b16 v119, v236 offset:39040
	ds_write_b16_d16_hi v119, v236 offset:39312
	ds_write_b16 v119, v237 offset:39584
	ds_write_b16_d16_hi v119, v237 offset:39856
	ds_write_b16 v119, v238 offset:40128
	ds_write_b16_d16_hi v119, v238 offset:40400
	ds_write_b16 v119, v239 offset:40672
	ds_write_b16_d16_hi v119, v239 offset:40944
	s_waitcnt vmcnt(17)
	ds_write_b16 v119, v240 offset:41216
	ds_write_b16_d16_hi v119, v240 offset:41488
	ds_write_b16 v119, v241 offset:41760
	ds_write_b16_d16_hi v119, v241 offset:42032
	ds_write_b16 v119, v242 offset:42304
	ds_write_b16_d16_hi v119, v242 offset:42576
	ds_write_b16 v119, v243 offset:42848
	ds_write_b16_d16_hi v119, v243 offset:43120
	s_waitcnt vmcnt(16)
	ds_write_b16 v119, v244 offset:43392
	ds_write_b16_d16_hi v119, v244 offset:43664
	ds_write_b16 v119, v245 offset:43936
	ds_write_b16_d16_hi v119, v245 offset:44208
	ds_write_b16 v119, v246 offset:44480
	ds_write_b16_d16_hi v119, v246 offset:44752
	ds_write_b16 v119, v247 offset:45024
	ds_write_b16_d16_hi v119, v247 offset:45296
	s_waitcnt lgkmcnt(0)
	s_waitcnt lgkmcnt(0)
	s_barrier
	ds_read_b128 v[72:75], v162
	ds_read_b128 v[68:71], v162 offset:64
	ds_read_b128 v[76:79], v163 offset:18432
	ds_read_b128 v[80:83], v163 offset:18496
	s_waitcnt lgkmcnt(1)
	v_mfma_f32_16x16x32_bf16 v[76:79], v[72:75], v[76:79], 0
	v_add_u32_e32 v109, 0xffffa7c0, v161
	s_waitcnt lgkmcnt(0)
	v_mfma_f32_16x16x32_bf16 v[76:79], v[68:71], v[80:83], v[76:79]
	v_mul_f32_e32 v80, v84, v121
	v_exp_f32_e32 v80, v80
	s_waitcnt vmcnt(0)
	v_mfma_f32_16x16x32_bf16 v[4:7], v[72:75], v[4:7], 0
	v_mfma_f32_16x16x32_bf16 v[8:11], v[72:75], v[8:11], 0
	s_nop 3
	v_mul_f32_e32 v76, v80, v76
	v_cvt_pk_bf16_f32 v76, v76, s0
	ds_write_b16 v167, v76
	v_mul_f32_e32 v76, v84, v122
	v_exp_f32_e32 v76, v76
	v_mfma_f32_16x16x32_bf16 v[4:7], v[68:71], v[16:19], v[4:7]
	v_mul_f32_e32 v76, v76, v77
	v_cvt_pk_bf16_f32 v76, v76, s0
	ds_write_b16 v167, v76 offset:272
	v_mul_f32_e32 v76, v84, v123
	v_exp_f32_e32 v76, v76
	v_mfma_f32_16x16x32_bf16 v[16:19], v[68:71], v[24:27], v[8:11]
	v_mul_f32_e32 v76, v76, v78
	v_cvt_pk_bf16_f32 v76, v76, s0
	ds_write_b16 v167, v76 offset:544
	v_mul_f32_e32 v76, v84, v124
	v_exp_f32_e32 v76, v76
	v_mfma_f32_16x16x32_bf16 v[10:13], v[72:75], v[12:15], 0
	v_mul_f32_e32 v76, v76, v79
	v_cvt_pk_bf16_f32 v76, v76, s0
	ds_write_b16 v167, v76 offset:816
	ds_read_b128 v[76:79], v163 offset:20736
	ds_read_b128 v[80:83], v163 offset:20800
	s_waitcnt lgkmcnt(1)
	v_mfma_f32_16x16x32_bf16 v[76:79], v[72:75], v[76:79], 0
	s_waitcnt lgkmcnt(0)
	v_mfma_f32_16x16x32_bf16 v[76:79], v[68:71], v[80:83], v[76:79]
	v_mul_f32_e32 v80, v84, v125
	v_exp_f32_e32 v80, v80
	v_mfma_f32_16x16x32_bf16 v[10:13], v[68:71], v[32:35], v[10:13]
	s_nop 4
	v_mul_f32_e32 v76, v80, v76
	v_cvt_pk_bf16_f32 v76, v76, s0
	ds_write_b16 v167, v76 offset:32
	v_mul_f32_e32 v76, v84, v126
	v_exp_f32_e32 v76, v76
	s_nop 0
	v_mul_f32_e32 v76, v76, v77
	v_cvt_pk_bf16_f32 v76, v76, s0
	ds_write_b16 v167, v76 offset:304
	v_mul_f32_e32 v76, v84, v127
	v_exp_f32_e32 v76, v76
	s_nop 0
	v_mul_f32_e32 v76, v76, v78
	v_cvt_pk_bf16_f32 v76, v76, s0
	ds_write_b16 v167, v76 offset:576
	v_mul_f32_e32 v76, v84, v128
	v_exp_f32_e32 v76, v76
	s_nop 0
	v_mul_f32_e32 v76, v76, v79
	v_cvt_pk_bf16_f32 v76, v76, s0
	ds_write_b16 v167, v76 offset:848
	ds_read_b128 v[76:79], v163 offset:23040
	ds_read_b128 v[80:83], v163 offset:23104
	s_waitcnt lgkmcnt(1)
; #define LAS __attribute__((address_space(3)))
; #define LDS_WAIT() asm volatile("s_waitcnt lgkmcnt(0)" ::: "memory")
; __device__ __forceinline__ unsigned f2bf(float f) { return cvtpk(f, 0.f) & 0xffffu; }
; #define MFMA16(a, b, c) __builtin_amdgcn_mfma_f32_16x16x32_bf16((a), (b), (c), 0, 0, 0)
; __device__ __forceinline__ void ret_out_phase(int l, LAS unsigned char* lds, int wave, int lane_) {
;     ...
;         for (int nb = 0; nb < 8; ++nb) {
;             f32x4 sc = {0.f, 0.f, 0.f, 0.f};
; #pragma unroll
;             for (int ks = 0; ks < 2; ++ks) { const bf16x8 bk = *(const LAS bf16x8*)(Ks + (nb * 16 + fr) * QP + 32 * ks + 8 * fq); sc = MFMA16(aq[ks], bk, sc); }
; #pragma unroll
;             for (int i = 0; i < 4; ++i) { const int n = 16 * wave + 4 * fq + i, mk = nb * 16 + fr; const int d = n > mk ? n - mk : mk - n;
;                 Pw[(4 * fq + i) * KP + mk] = (bf16)f2bf(sc[i] * __builtin_amdgcn_exp2f(l2g * (float)d)); }
;         }
;         LDS_WAIT(); asm volatile("" ::: "memory");
;         f32x4 y1[8];
;         f32x4 xfv, xbv;
; #pragma unroll
;         for (int i = 0; i < 4; ++i) { const int nl = 16 * wave + 4 * fq + i; xfv[i] = __builtin_amdgcn_exp2f(l2g * (float)(nl + 1)); xbv[i] = __builtin_amdgcn_exp2f(l2g * (float)(RC - nl)); }
	v_mfma_f32_16x16x32_bf16 v[76:79], v[72:75], v[76:79], 0
	s_waitcnt lgkmcnt(0)
	v_mfma_f32_16x16x32_bf16 v[76:79], v[68:71], v[80:83], v[76:79]
	v_mul_f32_e32 v80, v84, v129
	v_exp_f32_e32 v80, v80
	s_nop 5
	v_mul_f32_e32 v76, v80, v76
	v_cvt_pk_bf16_f32 v76, v76, s0
	ds_write_b16 v167, v76 offset:64
	v_mul_f32_e32 v76, v84, v130
	v_exp_f32_e32 v76, v76
	s_nop 0
	v_mul_f32_e32 v76, v76, v77
	v_cvt_pk_bf16_f32 v76, v76, s0
	ds_write_b16 v167, v76 offset:336
	v_mul_f32_e32 v76, v84, v131
	v_exp_f32_e32 v76, v76
	s_nop 0
	v_mul_f32_e32 v76, v76, v78
	v_cvt_pk_bf16_f32 v76, v76, s0
	ds_write_b16 v167, v76 offset:608
	v_mul_f32_e32 v76, v84, v132
	v_exp_f32_e32 v76, v76
	s_nop 0
	v_mul_f32_e32 v76, v76, v79
	v_cvt_pk_bf16_f32 v76, v76, s0
	ds_write_b16 v167, v76 offset:880
	ds_read_b128 v[76:79], v163 offset:25344
	ds_read_b128 v[80:83], v163 offset:25408
	s_waitcnt lgkmcnt(1)
	v_mfma_f32_16x16x32_bf16 v[76:79], v[72:75], v[76:79], 0
	s_waitcnt lgkmcnt(0)
	v_mfma_f32_16x16x32_bf16 v[76:79], v[68:71], v[80:83], v[76:79]
	v_mul_f32_e32 v80, v84, v133
	v_exp_f32_e32 v80, v80
	s_nop 5
	v_mul_f32_e32 v76, v80, v76
	v_cvt_pk_bf16_f32 v76, v76, s0
	ds_write_b16 v167, v76 offset:96
	v_mul_f32_e32 v76, v84, v134
	v_exp_f32_e32 v76, v76
	s_nop 0
	v_mul_f32_e32 v76, v76, v77
	v_cvt_pk_bf16_f32 v76, v76, s0
	ds_write_b16 v167, v76 offset:368
	v_mul_f32_e32 v76, v84, v135
	v_exp_f32_e32 v76, v76
	s_nop 0
	v_mul_f32_e32 v76, v76, v78
	v_cvt_pk_bf16_f32 v76, v76, s0
	ds_write_b16 v167, v76 offset:640
	v_mul_f32_e32 v76, v84, v136
	v_exp_f32_e32 v76, v76
	s_nop 0
	v_mul_f32_e32 v76, v76, v79
	v_cvt_pk_bf16_f32 v76, v76, s0
	ds_write_b16 v167, v76 offset:912
	ds_read_b128 v[76:79], v163 offset:27648
	ds_read_b128 v[80:83], v163 offset:27712
	s_waitcnt lgkmcnt(1)
	v_mfma_f32_16x16x32_bf16 v[76:79], v[72:75], v[76:79], 0
	s_waitcnt lgkmcnt(0)
	v_mfma_f32_16x16x32_bf16 v[76:79], v[68:71], v[80:83], v[76:79]
	v_mul_f32_e32 v80, v84, v137
	v_exp_f32_e32 v80, v80
	s_nop 5
	v_mul_f32_e32 v76, v80, v76
	v_cvt_pk_bf16_f32 v76, v76, s0
	ds_write_b16 v167, v76 offset:128
	v_mul_f32_e32 v76, v84, v138
	v_exp_f32_e32 v76, v76
	s_nop 0
	v_mul_f32_e32 v76, v76, v77
	v_cvt_pk_bf16_f32 v76, v76, s0
	ds_write_b16 v167, v76 offset:400
	v_mul_f32_e32 v76, v84, v139
	v_exp_f32_e32 v76, v76
	s_nop 0
	v_mul_f32_e32 v76, v76, v78
	v_cvt_pk_bf16_f32 v76, v76, s0
	ds_write_b16 v167, v76 offset:672
	v_mul_f32_e32 v76, v84, v140
	v_exp_f32_e32 v76, v76
	s_nop 0
	v_mul_f32_e32 v76, v76, v79
	v_cvt_pk_bf16_f32 v76, v76, s0
	ds_write_b16 v167, v76 offset:944
	ds_read_b128 v[76:79], v163 offset:29952
	ds_read_b128 v[80:83], v163 offset:30016
	s_waitcnt lgkmcnt(1)
	v_mfma_f32_16x16x32_bf16 v[76:79], v[72:75], v[76:79], 0
	s_waitcnt lgkmcnt(0)
	v_mfma_f32_16x16x32_bf16 v[76:79], v[68:71], v[80:83], v[76:79]
	v_mul_f32_e32 v80, v84, v141
	v_exp_f32_e32 v80, v80
	s_nop 5
	v_mul_f32_e32 v76, v80, v76
	v_cvt_pk_bf16_f32 v76, v76, s0
	ds_write_b16 v167, v76 offset:160
	v_mul_f32_e32 v76, v84, v142
	v_exp_f32_e32 v76, v76
	s_nop 0
	v_mul_f32_e32 v76, v76, v77
	v_cvt_pk_bf16_f32 v76, v76, s0
	ds_write_b16 v167, v76 offset:432
	v_mul_f32_e32 v76, v84, v143
	v_exp_f32_e32 v76, v76
	s_nop 0
	v_mul_f32_e32 v76, v76, v78
	v_cvt_pk_bf16_f32 v76, v76, s0
	ds_write_b16 v167, v76 offset:704
	v_mul_f32_e32 v76, v84, v144
	v_exp_f32_e32 v76, v76
	s_nop 0
	v_mul_f32_e32 v76, v76, v79
	v_cvt_pk_bf16_f32 v76, v76, s0
	ds_write_b16 v167, v76 offset:976
	ds_read_b128 v[76:79], v163 offset:32256
	ds_read_b128 v[80:83], v163 offset:32320
	s_waitcnt lgkmcnt(1)
	v_mfma_f32_16x16x32_bf16 v[76:79], v[72:75], v[76:79], 0
	s_waitcnt lgkmcnt(0)
	v_mfma_f32_16x16x32_bf16 v[76:79], v[68:71], v[80:83], v[76:79]
	v_mul_f32_e32 v80, v84, v145
	v_exp_f32_e32 v80, v80
	s_nop 5
	v_mul_f32_e32 v76, v80, v76
	v_cvt_pk_bf16_f32 v76, v76, s0
	ds_write_b16 v167, v76 offset:192
	v_mul_f32_e32 v76, v84, v146
	v_exp_f32_e32 v76, v76
	s_nop 0
	v_mul_f32_e32 v76, v76, v77
	v_cvt_pk_bf16_f32 v76, v76, s0
	ds_write_b16 v167, v76 offset:464
	v_mul_f32_e32 v76, v84, v147
	v_exp_f32_e32 v76, v76
	s_nop 0
	v_mul_f32_e32 v76, v76, v78
	v_cvt_pk_bf16_f32 v76, v76, s0
	ds_write_b16 v167, v76 offset:736
	v_mul_f32_e32 v76, v84, v148
	v_exp_f32_e32 v76, v76
	s_nop 0
	v_mul_f32_e32 v76, v76, v79
	v_cvt_pk_bf16_f32 v76, v76, s0
	ds_write_b16 v167, v76 offset:1008
	ds_read_b128 v[76:79], v163 offset:34560
	ds_read_b128 v[80:83], v163 offset:34624
	s_waitcnt lgkmcnt(1)
	v_mfma_f32_16x16x32_bf16 v[76:79], v[72:75], v[76:79], 0
	s_waitcnt lgkmcnt(0)
	v_mfma_f32_16x16x32_bf16 v[76:79], v[68:71], v[80:83], v[76:79]
	v_mul_f32_e32 v80, v84, v149
	v_exp_f32_e32 v80, v80
	s_nop 5
	v_mul_f32_e32 v76, v80, v76
	v_cvt_pk_bf16_f32 v76, v76, s0
	ds_write_b16 v167, v76 offset:224
	v_mul_f32_e32 v76, v84, v150
	v_exp_f32_e32 v76, v76
	s_nop 0
	v_mul_f32_e32 v76, v76, v77
	v_cvt_pk_bf16_f32 v76, v76, s0
	ds_write_b16 v167, v76 offset:496
	v_mul_f32_e32 v76, v84, v151
	v_exp_f32_e32 v76, v76
	s_nop 0
	v_mul_f32_e32 v76, v76, v78
	v_cvt_pk_bf16_f32 v76, v76, s0
	ds_write_b16 v167, v76 offset:768
	v_mul_f32_e32 v76, v84, v152
	v_exp_f32_e32 v76, v76
	s_nop 0
	v_mul_f32_e32 v76, v76, v79
	v_cvt_pk_bf16_f32 v76, v76, s0
	ds_write_b16 v167, v76 offset:1040
	v_mul_f32_e32 v76, v84, v153
	v_exp_f32_e32 v112, v76
	v_mul_f32_e32 v76, v84, v154
	v_exp_f32_e32 v110, v76
	v_mul_f32_e32 v76, v84, v155
	v_exp_f32_e32 v113, v76
	v_mul_f32_e32 v76, v84, v156
	v_exp_f32_e32 v111, v76
	v_mul_f32_e32 v76, v84, v157
	v_exp_f32_e32 v116, v76
	v_mul_f32_e32 v76, v84, v158
	v_exp_f32_e32 v114, v76
	v_mul_f32_e32 v76, v84, v159
	s_waitcnt lgkmcnt(0)
; #define LAS __attribute__((address_space(3)))
; #define MFMA16(a, b, c) __builtin_amdgcn_mfma_f32_16x16x32_bf16((a), (b), (c), 0, 0, 0)
; __device__ __forceinline__ void ret_out_phase(int l, LAS unsigned char* lds, int wave, int lane_) {
;     ...
;         bf16x8 ap[4];
; #pragma unroll
;         for (int ks = 0; ks < 4; ++ks) ap[ks] = *(const LAS bf16x8*)(Pw + fr * KP + 32 * ks + 8 * fq);
; #pragma unroll
;         for (int g = 0; g < 2; ++g) {
;             if (g == 1) { RET_LD_STATES(1); }
; #pragma unroll
;             for (int o4 = 0; o4 < 4; ++o4) {
;                 const int ob = 4 * g + o4;
;                 f32x4 y2 = {0.f, 0.f, 0.f, 0.f}, y3 = y2; y1[ob] = y2;
; #pragma unroll
;                 for (int ks = 0; ks < 4; ++ks) { const bf16x8 bvv = *(const LAS bf16x8*)(Vt + (ob * 16 + fr) * KP + 32 * ks + 8 * fq); y1[ob] = MFMA16(ap[ks], bvv, y1[ob]); }
; #pragma unroll
;                 for (int ks = 0; ks < 2; ++ks) { y2 = MFMA16(aq[ks], __builtin_bit_cast(bf16x8, sfv[o4][ks]), y2); y3 = MFMA16(aq[ks], __builtin_bit_cast(bf16x8, sbv[o4][ks]), y3); }
;                 y1[ob] = y1[ob] + xfv * y2 + xbv * y3;
;             }
	v_exp_f32_e32 v117, v76
	v_mul_f32_e32 v76, v84, v160
	v_exp_f32_e32 v115, v76
	v_add_u32_e32 v76, v120, v93
	ds_read_b128 v[88:91], v76
	ds_read_b128 v[84:87], v76 offset:64
	ds_read_b128 v[80:83], v76 offset:128
	ds_read_b128 v[76:79], v76 offset:192
	ds_read_b128 v[182:185], v168 offset:36864
	ds_read_b128 v[186:189], v168 offset:36928
	s_waitcnt lgkmcnt(1)
	v_mfma_f32_16x16x32_bf16 v[182:185], v[88:91], v[182:185], 0
	s_waitcnt lgkmcnt(0)
	v_mfma_f32_16x16x32_bf16 v[182:185], v[84:87], v[186:189], v[182:185]
	ds_read_b128 v[186:189], v168 offset:36992
	s_waitcnt lgkmcnt(0)
	v_mfma_f32_16x16x32_bf16 v[182:185], v[80:83], v[186:189], v[182:185]
	ds_read_b128 v[186:189], v168 offset:37056
	s_waitcnt lgkmcnt(0)
	v_mfma_f32_16x16x32_bf16 v[182:185], v[76:79], v[186:189], v[182:185]
	s_nop 7
	v_pk_fma_f32 v[6:7], v[116:117], v[6:7], v[184:185]
	v_pk_fma_f32 v[4:5], v[112:113], v[4:5], v[182:183]
	v_pk_fma_f32 v[8:9], v[114:115], v[18:19], v[6:7]
	v_pk_fma_f32 v[24:25], v[110:111], v[16:17], v[4:5]
	ds_read_b128 v[4:7], v180 offset:36864
	ds_read_b128 v[16:19], v180 offset:36928
	s_waitcnt lgkmcnt(1)
	v_mfma_f32_16x16x32_bf16 v[4:7], v[88:91], v[4:7], 0
	s_waitcnt lgkmcnt(0)
	v_mfma_f32_16x16x32_bf16 v[4:7], v[84:87], v[16:19], v[4:7]
	ds_read_b128 v[16:19], v180 offset:36992
	s_waitcnt lgkmcnt(0)
	v_mfma_f32_16x16x32_bf16 v[4:7], v[80:83], v[16:19], v[4:7]
	ds_read_b128 v[16:19], v180 offset:37056
	s_waitcnt lgkmcnt(0)
	v_mfma_f32_16x16x32_bf16 v[4:7], v[76:79], v[16:19], v[4:7]
	v_mfma_f32_16x16x32_bf16 v[14:17], v[72:75], v[20:23], 0
	s_nop 6
	v_fma_f32 v6, v116, v12, v6
	v_fma_f32 v7, v117, v13, v7
	v_pk_fma_f32 v[4:5], v[112:113], v[10:11], v[4:5]
	v_mfma_f32_16x16x32_bf16 v[14:17], v[68:71], v[40:43], v[14:17]
	s_nop 7
	v_pk_fma_f32 v[10:11], v[114:115], v[16:17], v[6:7]
	v_pk_fma_f32 v[22:23], v[110:111], v[14:15], v[4:5]
	ds_read_b128 v[4:7], v180 offset:41216
	ds_read_b128 v[12:15], v180 offset:41280
	s_waitcnt lgkmcnt(1)
	v_mfma_f32_16x16x32_bf16 v[4:7], v[88:91], v[4:7], 0
	s_waitcnt lgkmcnt(0)
	v_mfma_f32_16x16x32_bf16 v[4:7], v[84:87], v[12:15], v[4:7]
	ds_read_b128 v[12:15], v180 offset:41344
	s_waitcnt lgkmcnt(0)
	v_mfma_f32_16x16x32_bf16 v[4:7], v[80:83], v[12:15], v[4:7]
	ds_read_b128 v[12:15], v180 offset:41408
	s_waitcnt lgkmcnt(0)
	v_mfma_f32_16x16x32_bf16 v[4:7], v[76:79], v[12:15], v[4:7]
	v_mfma_f32_16x16x32_bf16 v[12:15], v[72:75], v[28:31], 0
	v_mfma_f32_16x16x32_bf16 v[16:19], v[72:75], v[36:39], 0
	v_mfma_f32_16x16x32_bf16 v[12:15], v[68:71], v[48:51], v[12:15]
	v_mfma_f32_16x16x32_bf16 v[16:19], v[68:71], v[56:59], v[16:19]
	s_nop 6
	v_fma_f32 v6, v116, v14, v6
	v_fma_f32 v7, v117, v15, v7
	v_pk_fma_f32 v[4:5], v[112:113], v[12:13], v[4:5]
	v_pk_fma_f32 v[12:13], v[114:115], v[18:19], v[6:7]
	v_pk_fma_f32 v[26:27], v[110:111], v[16:17], v[4:5]
	ds_read_b128 v[4:7], v180 offset:45568
	ds_read_b128 v[14:17], v180 offset:45632
	s_waitcnt lgkmcnt(1)
	v_mfma_f32_16x16x32_bf16 v[4:7], v[88:91], v[4:7], 0
	s_waitcnt lgkmcnt(0)
	v_mfma_f32_16x16x32_bf16 v[4:7], v[84:87], v[14:17], v[4:7]
	ds_read_b128 v[14:17], v180 offset:45696
	s_waitcnt lgkmcnt(0)
	v_mfma_f32_16x16x32_bf16 v[4:7], v[80:83], v[14:17], v[4:7]
	ds_read_b128 v[14:17], v180 offset:45760
	s_waitcnt lgkmcnt(0)
	v_mfma_f32_16x16x32_bf16 v[4:7], v[76:79], v[14:17], v[4:7]
	v_mfma_f32_16x16x32_bf16 v[14:17], v[72:75], v[44:47], 0
	v_mfma_f32_16x16x32_bf16 v[18:21], v[72:75], v[52:55], 0
	v_mfma_f32_16x16x32_bf16 v[14:17], v[68:71], v[60:63], v[14:17]
	v_mfma_f32_16x16x32_bf16 v[18:21], v[68:71], v[64:67], v[18:21]
	s_nop 6
	v_fma_f32 v6, v116, v16, v6
	v_fma_f32 v7, v117, v17, v7
	v_pk_fma_f32 v[4:5], v[112:113], v[14:15], v[4:5]
	v_add_u32_e32 v16, 0xffffc000, v161
	v_pk_fma_f32 v[14:15], v[114:115], v[20:21], v[6:7]
	v_pk_fma_f32 v[28:29], v[110:111], v[18:19], v[4:5]
	buffer_load_dwordx4 v[4:7], v161, s[60:63], 0 offen sc0 sc1
	buffer_load_dwordx4 v[38:41], v16, s[60:63], 0 offen sc0 sc1
	v_add_u32_e32 v16, 0xffffbfc0, v161
	v_subrev_u32_e32 v17, 64, v161
	buffer_load_dwordx4 v[42:45], v17, s[60:63], 0 offen sc0 sc1
	buffer_load_dwordx4 v[46:49], v16, s[60:63], 0 offen sc0 sc1
	v_add_u32_e32 v16, 0xfffff800, v161
	buffer_load_dwordx4 v[50:53], v16, s[60:63], 0 offen sc0 sc1
	v_add_u32_e32 v16, 0xffffb800, v161
	buffer_load_dwordx4 v[54:57], v16, s[60:63], 0 offen sc0 sc1
	v_add_u32_e32 v16, 0xffffb7c0, v161
	v_add_u32_e32 v17, 0xfffff7c0, v161
	buffer_load_dwordx4 v[58:61], v17, s[60:63], 0 offen sc0 sc1
	buffer_load_dwordx4 v[62:65], v16, s[60:63], 0 offen sc0 sc1
	v_add_u32_e32 v16, 0xfffff000, v161
	buffer_load_dwordx4 v[18:21], v16, s[60:63], 0 offen sc0 sc1
	v_add_u32_e32 v16, 0xffffb000, v161
	buffer_load_dwordx4 v[34:37], v16, s[60:63], 0 offen sc0 sc1
	v_add_u32_e32 v16, 0xffffafc0, v161
	v_add_u32_e32 v17, 0xffffefc0, v161
	buffer_load_dwordx4 v[182:185], v17, s[60:63], 0 offen sc0 sc1
	buffer_load_dwordx4 v[186:189], v16, s[60:63], 0 offen sc0 sc1
	v_add_u32_e32 v16, 0xffffe800, v161
	buffer_load_dwordx4 v[30:33], v16, s[60:63], 0 offen sc0 sc1
	v_add_u32_e32 v16, 0xffffa800, v161
	buffer_load_dwordx4 v[190:193], v16, s[60:63], 0 offen sc0 sc1
	v_add_u32_e32 v16, 0xffffe7c0, v161
	buffer_load_dwordx4 v[194:197], v16, s[60:63], 0 offen sc0 sc1
	buffer_load_dwordx4 v[208:211], v109, s[60:63], 0 offen sc0 sc1
	ds_read_b128 v[212:215], v180 offset:49920
	ds_read_b128 v[216:219], v180 offset:49984
	s_waitcnt lgkmcnt(1)
	v_mfma_f32_16x16x32_bf16 v[212:215], v[88:91], v[212:215], 0
	v_add_u32_e32 v161, s27, v161
	s_waitcnt lgkmcnt(0)
	v_mfma_f32_16x16x32_bf16 v[212:215], v[84:87], v[216:219], v[212:215]
	ds_read_b128 v[216:219], v180 offset:50048
	s_waitcnt vmcnt(1)
; #define LAS __attribute__((address_space(3)))
; #define MFMA16(a, b, c) __builtin_amdgcn_mfma_f32_16x16x32_bf16((a), (b), (c), 0, 0, 0)
; __device__ __forceinline__ void ret_out_phase(int l, LAS unsigned char* lds, int wave, int lane_) {
;     ...
;         for (int g = 0; g < 2; ++g) {
;             if (g == 1) { RET_LD_STATES(1); }
; #pragma unroll
;             for (int o4 = 0; o4 < 4; ++o4) {
;                 const int ob = 4 * g + o4;
;                 f32x4 y2 = {0.f, 0.f, 0.f, 0.f}, y3 = y2; y1[ob] = y2;
; #pragma unroll
;                 for (int ks = 0; ks < 4; ++ks) { const bf16x8 bvv = *(const LAS bf16x8*)(Vt + (ob * 16 + fr) * KP + 32 * ks + 8 * fq); y1[ob] = MFMA16(ap[ks], bvv, y1[ob]); }
; #pragma unroll
;                 for (int ks = 0; ks < 2; ++ks) { y2 = MFMA16(aq[ks], __builtin_bit_cast(bf16x8, sfv[o4][ks]), y2); y3 = MFMA16(aq[ks], __builtin_bit_cast(bf16x8, sbv[o4][ks]), y3); }
;                 y1[ob] = y1[ob] + xfv * y2 + xbv * y3;
;             }
;             asm volatile("" ::: "memory");
;         }
; #pragma unroll
;         for (int i = 0; i < 4; ++i) {
;             const int nl = 16 * wave + 4 * fq + i;
;             float v[8]; float s = 0.f;
; #pragma unroll
;             for (int ob = 0; ob < 8; ++ob) { v[ob] = y1[ob][i]; s += v[ob]; }
;             s += __shfl_xor(s, 1); s += __shfl_xor(s, 2); s += __shfl_xor(s, 4); s += __shfl_xor(s, 8);
;             const float mean = s * (1.f / 128.f); float q = 0.f;
; #pragma unroll
;             for (int ob = 0; ob < 8; ++ob) { v[ob] -= mean; q += v[ob] * v[ob]; }
;             q += __shfl_xor(q, 1); q += __shfl_xor(q, 2); q += __shfl_xor(q, 4); q += __shfl_xor(q, 8);
	v_mfma_f32_16x16x32_bf16 v[194:197], v[72:75], v[194:197], 0
	v_mfma_f32_16x16x32_bf16 v[30:33], v[68:71], v[30:33], v[194:197]
	s_nop 6
	ds_read_b128 v[194:197], v180 offset:54336
	s_waitcnt lgkmcnt(1)
	v_mfma_f32_16x16x32_bf16 v[212:215], v[80:83], v[216:219], v[212:215]
	ds_read_b128 v[216:219], v180 offset:50112
	s_waitcnt vmcnt(0)
	v_mfma_f32_16x16x32_bf16 v[208:211], v[72:75], v[208:211], 0
	v_mfma_f32_16x16x32_bf16 v[186:189], v[72:75], v[186:189], 0
	v_mfma_f32_16x16x32_bf16 v[190:193], v[68:71], v[190:193], v[208:211]
	v_mfma_f32_16x16x32_bf16 v[34:37], v[68:71], v[34:37], v[186:189]
	s_nop 5
	ds_read_b128 v[186:189], v180 offset:58688
	s_waitcnt lgkmcnt(1)
	v_mfma_f32_16x16x32_bf16 v[212:215], v[76:79], v[216:219], v[212:215]
	v_mfma_f32_16x16x32_bf16 v[182:185], v[72:75], v[182:185], 0
	v_mfma_f32_16x16x32_bf16 v[182:185], v[68:71], v[18:21], v[182:185]
	s_nop 5
	v_fma_f32 v16, v116, v192, v214
	v_fma_f32 v17, v117, v193, v215
	v_pk_fma_f32 v[66:67], v[112:113], v[190:191], v[212:213]
	ds_read_b128 v[190:193], v180 offset:54272
	s_waitcnt lgkmcnt(0)
	v_mfma_f32_16x16x32_bf16 v[190:193], v[88:91], v[190:193], 0
	v_fma_f32 v16, v114, v32, v16
	v_fma_f32 v17, v115, v33, v17
	v_pk_fma_f32 v[32:33], v[110:111], v[30:31], v[66:67]
	v_mfma_f32_16x16x32_bf16 v[190:193], v[84:87], v[194:197], v[190:193]
	ds_read_b128 v[194:197], v180 offset:54400
	s_waitcnt lgkmcnt(0)
	v_mfma_f32_16x16x32_bf16 v[190:193], v[80:83], v[194:197], v[190:193]
	ds_read_b128 v[194:197], v180 offset:54464
	s_waitcnt lgkmcnt(0)
	v_mfma_f32_16x16x32_bf16 v[190:193], v[76:79], v[194:197], v[190:193]
	v_mfma_f32_16x16x32_bf16 v[62:65], v[72:75], v[62:65], 0
	s_nop 6
	v_fma_f32 v18, v116, v36, v192
	v_fma_f32 v19, v117, v37, v193
	v_pk_fma_f32 v[20:21], v[112:113], v[34:35], v[190:191]
	v_pk_fma_f32 v[18:19], v[114:115], v[184:185], v[18:19]
	v_pk_fma_f32 v[34:35], v[110:111], v[182:183], v[20:21]
	ds_read_b128 v[182:185], v180 offset:58624
	s_waitcnt lgkmcnt(0)
	v_mfma_f32_16x16x32_bf16 v[182:185], v[88:91], v[182:185], 0
	v_mfma_f32_16x16x32_bf16 v[182:185], v[84:87], v[186:189], v[182:185]
	ds_read_b128 v[186:189], v180 offset:58752
	s_waitcnt lgkmcnt(0)
	v_mfma_f32_16x16x32_bf16 v[182:185], v[80:83], v[186:189], v[182:185]
	ds_read_b128 v[186:189], v180 offset:58816
	v_mfma_f32_16x16x32_bf16 v[58:61], v[72:75], v[58:61], 0
	s_waitcnt lgkmcnt(0)
	v_mfma_f32_16x16x32_bf16 v[182:185], v[76:79], v[186:189], v[182:185]
	v_mfma_f32_16x16x32_bf16 v[54:57], v[68:71], v[54:57], v[62:65]
	v_mfma_f32_16x16x32_bf16 v[50:53], v[68:71], v[50:53], v[58:61]
	v_mfma_f32_16x16x32_bf16 v[46:49], v[72:75], v[46:49], 0
	s_nop 5
	v_fma_f32 v20, v116, v56, v184
	v_fma_f32 v21, v117, v57, v185
	v_pk_fma_f32 v[30:31], v[112:113], v[54:55], v[182:183]
	v_pk_fma_f32 v[20:21], v[114:115], v[52:53], v[20:21]
	v_pk_fma_f32 v[36:37], v[110:111], v[50:51], v[30:31]
	ds_read_b128 v[50:53], v180 offset:62976
	ds_read_b128 v[54:57], v180 offset:63040
	s_waitcnt lgkmcnt(1)
	v_mfma_f32_16x16x32_bf16 v[50:53], v[88:91], v[50:53], 0
	v_mov_b32_e32 v61, v36
	s_waitcnt lgkmcnt(0)
	v_mfma_f32_16x16x32_bf16 v[50:53], v[84:87], v[54:57], v[50:53]
	ds_read_b128 v[54:57], v180 offset:63104
	s_waitcnt lgkmcnt(0)
	v_mfma_f32_16x16x32_bf16 v[50:53], v[80:83], v[54:57], v[50:53]
	ds_read_b128 v[54:57], v180 offset:63168
	s_load_dwordx2 s[48:49], s[30:31], 0x90
	v_mfma_f32_16x16x32_bf16 v[42:45], v[72:75], v[42:45], 0
	s_waitcnt lgkmcnt(0)
	s_add_u32 s43, s48, s26
	v_mfma_f32_16x16x32_bf16 v[50:53], v[76:79], v[54:57], v[50:53]
	s_addc_u32 s47, s49, 0
	s_lshl_b32 s42, s42, 9
	s_add_u32 s42, s43, s42
	v_mfma_f32_16x16x32_bf16 v[38:41], v[68:71], v[38:41], v[46:49]
	s_addc_u32 s43, s47, 0
	s_add_i32 s46, s46, s58
	s_add_i32 s29, s29, s28
	v_mfma_f32_16x16x32_bf16 v[4:7], v[68:71], v[4:7], v[42:45]
	s_cmpk_lt_i32 s46, 0x800
	s_nop 2
	v_pk_fma_f32 v[30:31], v[116:117], v[40:41], v[52:53]
	v_pk_fma_f32 v[38:39], v[112:113], v[38:39], v[50:51]
	v_lshlrev_b32_e32 v44, 2, v92
	global_load_dword v55, v44, s[42:43]
	global_load_dword v54, v44, s[42:43] offset:64
	global_load_dword v53, v44, s[42:43] offset:128
	global_load_dword v52, v44, s[42:43] offset:192
	global_load_dword v51, v44, s[42:43] offset:256
	global_load_dword v50, v44, s[42:43] offset:320
	global_load_dword v49, v44, s[42:43] offset:384
	global_load_dword v48, v44, s[42:43] offset:448
	v_pk_add_f32 v[44:45], v[24:25], 0 op_sel_hi:[1,0]
	v_pk_fma_f32 v[38:39], v[110:111], v[4:5], v[38:39]
	v_pk_add_f32 v[44:45], v[44:45], v[22:23]
	v_and_b32_e32 v5, 64, v198
	v_pk_add_f32 v[44:45], v[44:45], v[26:27]
	v_xor_b32_e32 v4, 1, v198
	v_pk_add_f32 v[44:45], v[44:45], v[28:29]
	v_add_u32_e32 v5, 64, v5
	v_pk_add_f32 v[44:45], v[44:45], v[32:33]
	v_cmp_lt_i32_e32 vcc, v4, v5
	v_pk_add_f32 v[44:45], v[44:45], v[34:35]
	v_pk_fma_f32 v[6:7], v[114:115], v[6:7], v[30:31]
	v_cndmask_b32_e32 v4, v198, v4, vcc
	v_mov_b32_e32 v30, v28
	v_mov_b32_e32 v31, v26
	v_mov_b32_e32 v26, v29
	v_pk_add_f32 v[28:29], v[44:45], v[36:37]
	v_lshlrev_b32_e32 v56, 2, v4
	v_pk_add_f32 v[28:29], v[28:29], v[38:39]
	v_xor_b32_e32 v4, 2, v198
	v_cmp_lt_i32_e32 vcc, v4, v5
	v_mov_b32_e32 v42, v34
	v_mov_b32_e32 v43, v32
	v_cndmask_b32_e32 v4, v198, v4, vcc
	v_lshlrev_b32_e32 v57, 2, v4
	s_waitcnt lgkmcnt(0)
	s_nop 1
	v_add_f32_dpp v28, v28, v28 quad_perm:[1,0,3,2] row_mask:0xf bank_mask:0xf
	v_add_f32_dpp v29, v29, v29 quad_perm:[1,0,3,2] row_mask:0xf bank_mask:0xf
	v_xor_b32_e32 v4, 4, v198
	v_cmp_lt_i32_e32 vcc, v4, v5
	v_mov_b32_e32 v32, v35
	v_mov_b32_e32 v36, v39
	v_cndmask_b32_e32 v4, v198, v4, vcc
	v_lshlrev_b32_e32 v58, 2, v4
	s_waitcnt lgkmcnt(0)
; __device__ __forceinline__ unsigned f2bf(float f) { return cvtpk(f, 0.f) & 0xffffu; }
; __device__ __forceinline__ void ret_out_phase(int l, LAS unsigned char* lds, int wave, int lane_) {
;     ...
;         for (int i = 0; i < 4; ++i) {
;             const int nl = 16 * wave + 4 * fq + i;
;             float v[8]; float s = 0.f;
; #pragma unroll
;             for (int ob = 0; ob < 8; ++ob) { v[ob] = y1[ob][i]; s += v[ob]; }
;             s += __shfl_xor(s, 1); s += __shfl_xor(s, 2); s += __shfl_xor(s, 4); s += __shfl_xor(s, 8);
;             const float mean = s * (1.f / 128.f); float q = 0.f;
; #pragma unroll
;             for (int ob = 0; ob < 8; ++ob) { v[ob] -= mean; q += v[ob] * v[ob]; }
;             q += __shfl_xor(q, 1); q += __shfl_xor(q, 2); q += __shfl_xor(q, 4); q += __shfl_xor(q, 8);
;             const float rstd = rsqrtf(q * (1.f / 128.f) + 1e-6f);
;             bf16* yo = (bf16*)(ws + OFF_YB) + ((size_t)b * SEQ + j * RC + nl) * DM + h * 128;
;             const float* gn = p->in[I_RG] + (size_t)l * DM + h * 128;
; #pragma unroll
;             for (int ob = 0; ob < 8; ++ob) yo[ob * 16 + fr] = (bf16)f2bf(v[ob] * rstd * gn[ob * 16 + fr]);
	s_nop 1
	v_add_f32_dpp v28, v28, v28 quad_perm:[2,3,0,1] row_mask:0xf bank_mask:0xf
	v_add_f32_dpp v29, v29, v29 quad_perm:[2,3,0,1] row_mask:0xf bank_mask:0xf
	v_xor_b32_e32 v4, 8, v198
	v_cmp_lt_i32_e32 vcc, v4, v5
	v_mov_b32_e32 v60, v38
	s_mov_b32 s42, 0x358637bd
	v_cndmask_b32_e32 v4, v198, v4, vcc
	v_lshlrev_b32_e32 v59, 2, v4
	s_waitcnt lgkmcnt(0)
	s_nop 1
	v_add_f32_dpp v28, v28, v28 row_half_mirror row_mask:0xf bank_mask:0xf
	v_add_f32_dpp v29, v29, v29 row_half_mirror row_mask:0xf bank_mask:0xf
	v_lshl_add_u64 v[4:5], s[34:35], 0, v[100:101]
	v_lshlrev_b64 v[4:5], 11, v[4:5]
	v_lshl_add_u64 v[40:41], s[36:37], 0, v[4:5]
	v_lshlrev_b32_e32 v4, 1, v92
	s_waitcnt lgkmcnt(0)
	s_nop 1
	v_add_f32_dpp v28, v28, v28 row_mirror row_mask:0xf bank_mask:0xf
	v_add_f32_dpp v29, v29, v29 row_mirror row_mask:0xf bank_mask:0xf
	v_mov_b32_e32 v5, v3
	v_pk_mul_f32 v[62:63], v[28:29], s[86:87] op_sel_hi:[1,0]
	v_lshl_add_u64 v[40:41], v[40:41], 0, v[4:5]
	v_pk_add_f32 v[46:47], v[30:31], v[62:63] op_sel_hi:[1,0] neg_lo:[0,1] neg_hi:[0,1]
	v_pk_fma_f32 v[30:31], v[28:29], s[86:87], v[24:25] op_sel_hi:[1,0,1] neg_lo:[1,0,0] neg_hi:[1,0,0]
	v_pk_fma_f32 v[28:29], v[28:29], s[86:87], v[22:23] op_sel_hi:[1,0,1] neg_lo:[1,0,0] neg_hi:[1,0,0]
	v_pk_add_f32 v[26:27], v[26:27], v[62:63] op_sel:[0,1] neg_lo:[0,1] neg_hi:[0,1]
	v_pk_mul_f32 v[64:65], v[46:47], v[46:47]
	v_pk_mul_f32 v[22:23], v[28:29], v[28:29]
	v_pk_mul_f32 v[70:71], v[26:27], v[26:27]
	v_pk_add_f32 v[44:45], v[42:43], v[62:63] op_sel_hi:[1,0] neg_lo:[0,1] neg_hi:[0,1]
	v_pk_fma_f32 v[68:69], v[30:31], v[30:31], v[22:23]
	v_pk_add_f32 v[24:25], v[32:33], v[62:63] op_sel:[0,1] neg_lo:[0,1] neg_hi:[0,1]
	v_pk_add_f32 v[22:23], v[36:37], v[62:63] op_sel:[0,1] neg_lo:[0,1] neg_hi:[0,1]
	v_mov_b32_e32 v37, v64
	v_mov_b32_e32 v64, v71
	v_pk_mul_f32 v[66:67], v[44:45], v[44:45]
	v_pk_mul_f32 v[32:33], v[24:25], v[24:25]
	v_mov_b32_e32 v36, v70
	v_pk_add_f32 v[38:39], v[64:65], v[68:69] op_sel:[0,1] op_sel_hi:[1,0]
	v_pk_add_f32 v[42:43], v[60:61], v[62:63] op_sel_hi:[1,0] neg_lo:[0,1] neg_hi:[0,1]
	v_pk_add_f32 v[36:37], v[36:37], v[38:39]
	v_mov_b32_e32 v38, v33
	v_mov_b32_e32 v39, v67
	v_pk_mul_f32 v[60:61], v[42:43], v[42:43]
	v_pk_mul_f32 v[34:35], v[22:23], v[22:23]
	v_pk_add_f32 v[36:37], v[38:39], v[36:37]
	v_mov_b32_e32 v33, v66
	v_pk_add_f32 v[32:33], v[32:33], v[36:37]
	v_mov_b32_e32 v36, v35
	v_mov_b32_e32 v37, v61
	v_pk_add_f32 v[32:33], v[36:37], v[32:33]
	v_mov_b32_e32 v35, v60
	v_pk_add_f32 v[32:33], v[34:35], v[32:33]
	s_waitcnt lgkmcnt(0)
	s_nop 1
	v_add_f32_dpp v32, v32, v32 quad_perm:[1,0,3,2] row_mask:0xf bank_mask:0xf
	v_add_f32_dpp v33, v33, v33 quad_perm:[1,0,3,2] row_mask:0xf bank_mask:0xf
	s_waitcnt lgkmcnt(0)
	s_nop 1
	v_add_f32_dpp v32, v32, v32 quad_perm:[2,3,0,1] row_mask:0xf bank_mask:0xf
	v_add_f32_dpp v33, v33, v33 quad_perm:[2,3,0,1] row_mask:0xf bank_mask:0xf
	s_waitcnt lgkmcnt(0)
	s_nop 1
	v_add_f32_dpp v32, v32, v32 row_half_mirror row_mask:0xf bank_mask:0xf
	v_add_f32_dpp v33, v33, v33 row_half_mirror row_mask:0xf bank_mask:0xf
	s_waitcnt lgkmcnt(0)
	s_nop 1
	v_add_f32_dpp v34, v32, v32 row_mirror row_mask:0xf bank_mask:0xf
	v_add_f32_dpp v35, v33, v33 row_mirror row_mask:0xf bank_mask:0xf
	v_mov_b64_e32 v[32:33], s[42:43]
	v_pk_fma_f32 v[34:35], v[34:35], s[86:87], v[32:33] op_sel_hi:[1,0,0]
	s_nop 0
	v_mul_f32_e32 v36, 0x4b800000, v35
	v_cmp_gt_f32_e64 s[42:43], s19, v35
	v_cmp_gt_f32_e32 vcc, s19, v34
	s_nop 0
	v_cndmask_b32_e64 v35, v35, v36, s[42:43]
	v_rsq_f32_e32 v35, v35
	s_nop 0
	v_mul_f32_e32 v36, 0x45800000, v35
	v_cndmask_b32_e64 v35, v35, v36, s[42:43]
	v_mul_f32_e32 v28, v28, v35
	s_waitcnt vmcnt(0)
	v_mul_f32_e32 v28, v54, v28
	v_cvt_pk_bf16_f32 v28, v28, s0
	ds_write_b16 v167, v28 offset:32
	v_mul_f32_e32 v28, v47, v35
	s_waitcnt vmcnt(6)
	v_mul_f32_e32 v28, v53, v28
	v_cvt_pk_bf16_f32 v28, v28, s0
	ds_write_b16 v167, v28 offset:64
	v_mul_f32_e32 v28, v46, v35
	s_waitcnt vmcnt(6)
	v_mul_f32_e32 v28, v52, v28
	v_cvt_pk_bf16_f32 v28, v28, s0
	ds_write_b16 v167, v28 offset:96
	v_mul_f32_e32 v28, v45, v35
	s_waitcnt vmcnt(6)
	v_mul_f32_e32 v28, v51, v28
	v_cvt_pk_bf16_f32 v28, v28, s0
	ds_write_b16 v167, v28 offset:128
	v_mul_f32_e32 v28, v44, v35
	s_waitcnt vmcnt(6)
	v_mul_f32_e32 v28, v50, v28
	v_cvt_pk_bf16_f32 v28, v28, s0
	ds_write_b16 v167, v28 offset:160
	v_mul_f32_e32 v28, v43, v35
	s_waitcnt vmcnt(6)
	v_mul_f32_e32 v28, v49, v28
	v_cvt_pk_bf16_f32 v28, v28, s0
	ds_write_b16 v167, v28 offset:192
	v_mul_f32_e32 v28, v42, v35
	s_waitcnt vmcnt(6)
; __device__ __forceinline__ unsigned f2bf(float f) { return cvtpk(f, 0.f) & 0xffffu; }
; __device__ __forceinline__ void ret_out_phase(int l, LAS unsigned char* lds, int wave, int lane_) {
;     ...
;         for (int i = 0; i < 4; ++i) {
;             const int nl = 16 * wave + 4 * fq + i;
;             float v[8]; float s = 0.f;
; #pragma unroll
;             for (int ob = 0; ob < 8; ++ob) { v[ob] = y1[ob][i]; s += v[ob]; }
;             s += __shfl_xor(s, 1); s += __shfl_xor(s, 2); s += __shfl_xor(s, 4); s += __shfl_xor(s, 8);
;             const float mean = s * (1.f / 128.f); float q = 0.f;
; #pragma unroll
;             for (int ob = 0; ob < 8; ++ob) { v[ob] -= mean; q += v[ob] * v[ob]; }
;             q += __shfl_xor(q, 1); q += __shfl_xor(q, 2); q += __shfl_xor(q, 4); q += __shfl_xor(q, 8);
;             const float rstd = rsqrtf(q * (1.f / 128.f) + 1e-6f);
;             bf16* yo = (bf16*)(ws + OFF_YB) + ((size_t)b * SEQ + j * RC + nl) * DM + h * 128;
;             const float* gn = p->in[I_RG] + (size_t)l * DM + h * 128;
; #pragma unroll
;             for (int ob = 0; ob < 8; ++ob) yo[ob * 16 + fr] = (bf16)f2bf(v[ob] * rstd * gn[ob * 16 + fr]);
	v_mul_f32_e32 v28, v48, v28
	v_cvt_pk_bf16_f32 v28, v28, s0
	ds_write_b16 v167, v28 offset:224
	v_mul_f32_e32 v28, 0x4b800000, v34
	v_cndmask_b32_e32 v28, v34, v28, vcc
	v_rsq_f32_e32 v28, v28
	v_mul_f32_e32 v30, v30, v35
	v_mul_f32_e32 v30, v55, v30
	v_cvt_pk_bf16_f32 v30, v30, s0
	ds_write_b16 v167, v30 offset:0
	v_mul_f32_e32 v30, 0x45800000, v28
	v_cndmask_b32_e32 v28, v28, v30, vcc
	v_lshl_add_u64 v[34:35], s[34:35], 0, v[102:103]
	v_lshlrev_b64 v[34:35], 11, v[34:35]
	v_mul_f32_e32 v30, v31, v28
	v_mul_f32_e32 v29, v29, v28
	v_mul_f32_e32 v27, v27, v28
	v_mul_f32_e32 v26, v26, v28
	v_mul_f32_e32 v25, v25, v28
	v_mul_f32_e32 v24, v24, v28
	v_mul_f32_e32 v23, v23, v28
	v_mul_f32_e32 v22, v22, v28
	v_lshl_add_u64 v[34:35], s[36:37], 0, v[34:35]
	v_mul_f32_e32 v30, v55, v30
	v_mul_f32_e32 v29, v54, v29
	v_mul_f32_e32 v27, v53, v27
	v_mul_f32_e32 v26, v52, v26
	v_mul_f32_e32 v25, v51, v25
	v_mul_f32_e32 v24, v50, v24
	v_mul_f32_e32 v23, v49, v23
	v_mul_f32_e32 v22, v48, v22
	v_cvt_pk_bf16_f32 v36, v30, s0
	v_lshl_add_u64 v[30:31], v[34:35], 0, v[4:5]
	v_cvt_pk_bf16_f32 v29, v29, s0
	v_cvt_pk_bf16_f32 v27, v27, s0
	v_cvt_pk_bf16_f32 v26, v26, s0
	v_cvt_pk_bf16_f32 v25, v25, s0
	v_cvt_pk_bf16_f32 v24, v24, s0
	v_cvt_pk_bf16_f32 v23, v23, s0
	v_cvt_pk_bf16_f32 v22, v22, s0
	ds_write_b16 v167, v36 offset:272
	ds_write_b16 v167, v29 offset:304
	ds_write_b16 v167, v27 offset:336
	ds_write_b16 v167, v26 offset:368
	ds_write_b16 v167, v25 offset:400
	ds_write_b16 v167, v24 offset:432
	ds_write_b16 v167, v23 offset:464
	ds_write_b16 v167, v22 offset:496
	v_pk_add_f32 v[30:31], v[8:9], 0 op_sel_hi:[1,0]
	v_mov_b32_e32 v22, v14
	v_pk_add_f32 v[30:31], v[30:31], v[10:11]
	v_mov_b32_e32 v23, v12
	v_pk_add_f32 v[30:31], v[30:31], v[12:13]
	v_mov_b32_e32 v12, v15
	v_pk_add_f32 v[30:31], v[30:31], v[14:15]
	v_mov_b32_e32 v24, v18
	v_pk_add_f32 v[30:31], v[30:31], v[16:17]
	v_mov_b32_e32 v25, v16
	v_pk_add_f32 v[30:31], v[30:31], v[18:19]
	v_mov_b32_e32 v27, v20
	v_pk_add_f32 v[14:15], v[30:31], v[20:21]
	v_mov_b32_e32 v16, v19
	v_pk_add_f32 v[14:15], v[14:15], v[6:7]
	v_mov_b32_e32 v20, v7
	v_mov_b32_e32 v26, v6
	v_lshl_add_u64 v[28:29], s[34:35], 0, v[104:105]
	v_lshlrev_b64 v[28:29], 11, v[28:29]
	s_waitcnt lgkmcnt(0)
	s_nop 1
	v_add_f32_dpp v14, v14, v14 quad_perm:[1,0,3,2] row_mask:0xf bank_mask:0xf
	v_add_f32_dpp v15, v15, v15 quad_perm:[1,0,3,2] row_mask:0xf bank_mask:0xf
	v_lshl_add_u64 v[28:29], s[36:37], 0, v[28:29]
	v_lshl_add_u64 v[28:29], v[28:29], 0, v[4:5]
	s_waitcnt lgkmcnt(0)
	s_nop 1
	v_add_f32_dpp v14, v14, v14 quad_perm:[2,3,0,1] row_mask:0xf bank_mask:0xf
	v_add_f32_dpp v15, v15, v15 quad_perm:[2,3,0,1] row_mask:0xf bank_mask:0xf
	s_waitcnt lgkmcnt(0)
	s_nop 1
	v_add_f32_dpp v14, v14, v14 row_half_mirror row_mask:0xf bank_mask:0xf
	v_add_f32_dpp v15, v15, v15 row_half_mirror row_mask:0xf bank_mask:0xf
	s_waitcnt lgkmcnt(0)
	s_nop 1
	v_add_f32_dpp v14, v14, v14 row_mirror row_mask:0xf bank_mask:0xf
	v_add_f32_dpp v15, v15, v15 row_mirror row_mask:0xf bank_mask:0xf
	s_nop 0
	v_pk_mul_f32 v[30:31], v[14:15], s[86:87] op_sel_hi:[1,0]
	s_nop 0
	v_pk_add_f32 v[34:35], v[22:23], v[30:31] op_sel_hi:[1,0] neg_lo:[0,1] neg_hi:[0,1]
	v_pk_fma_f32 v[22:23], v[14:15], s[86:87], v[8:9] op_sel_hi:[1,0,1] neg_lo:[1,0,0] neg_hi:[1,0,0]
	v_pk_fma_f32 v[14:15], v[14:15], s[86:87], v[10:11] op_sel_hi:[1,0,1] neg_lo:[1,0,0] neg_hi:[1,0,0]
	v_pk_add_f32 v[10:11], v[12:13], v[30:31] op_sel:[0,1] neg_lo:[0,1] neg_hi:[0,1]
	v_pk_mul_f32 v[36:37], v[34:35], v[34:35]
	v_pk_mul_f32 v[8:9], v[14:15], v[14:15]
	v_pk_mul_f32 v[12:13], v[10:11], v[10:11]
	v_pk_add_f32 v[24:25], v[24:25], v[30:31] op_sel_hi:[1,0] neg_lo:[0,1] neg_hi:[0,1]
	v_pk_fma_f32 v[42:43], v[22:23], v[22:23], v[8:9]
	v_pk_add_f32 v[8:9], v[16:17], v[30:31] op_sel:[0,1] neg_lo:[0,1] neg_hi:[0,1]
	v_pk_add_f32 v[6:7], v[20:21], v[30:31] op_sel:[0,1] neg_lo:[0,1] neg_hi:[0,1]
	v_mov_b32_e32 v21, v36
	v_mov_b32_e32 v36, v13
	v_pk_mul_f32 v[38:39], v[24:25], v[24:25]
	v_pk_mul_f32 v[16:17], v[8:9], v[8:9]
	v_mov_b32_e32 v20, v12
	v_pk_add_f32 v[12:13], v[36:37], v[42:43] op_sel:[0,1] op_sel_hi:[1,0]
	v_pk_add_f32 v[26:27], v[26:27], v[30:31] op_sel_hi:[1,0] neg_lo:[0,1] neg_hi:[0,1]
	v_pk_add_f32 v[12:13], v[20:21], v[12:13]
	v_mov_b32_e32 v20, v17
	v_mov_b32_e32 v21, v39
	v_pk_mul_f32 v[40:41], v[26:27], v[26:27]
	v_pk_mul_f32 v[18:19], v[6:7], v[6:7]
	v_pk_add_f32 v[12:13], v[20:21], v[12:13]
	v_mov_b32_e32 v17, v38
	v_pk_add_f32 v[12:13], v[16:17], v[12:13]
	v_mov_b32_e32 v16, v19
	v_mov_b32_e32 v17, v41
	v_pk_add_f32 v[12:13], v[16:17], v[12:13]
	v_mov_b32_e32 v19, v40
	v_pk_add_f32 v[12:13], v[18:19], v[12:13]
	s_waitcnt lgkmcnt(0)
; __device__ __forceinline__ unsigned f2bf(float f) { return cvtpk(f, 0.f) & 0xffffu; }
; __device__ __forceinline__ void ret_out_phase(int l, LAS unsigned char* lds, int wave, int lane_) {
;     ...
;         for (int i = 0; i < 4; ++i) {
;             const int nl = 16 * wave + 4 * fq + i;
;             float v[8]; float s = 0.f;
; #pragma unroll
;             for (int ob = 0; ob < 8; ++ob) { v[ob] = y1[ob][i]; s += v[ob]; }
;             s += __shfl_xor(s, 1); s += __shfl_xor(s, 2); s += __shfl_xor(s, 4); s += __shfl_xor(s, 8);
;             const float mean = s * (1.f / 128.f); float q = 0.f;
; #pragma unroll
;             for (int ob = 0; ob < 8; ++ob) { v[ob] -= mean; q += v[ob] * v[ob]; }
;             q += __shfl_xor(q, 1); q += __shfl_xor(q, 2); q += __shfl_xor(q, 4); q += __shfl_xor(q, 8);
;             const float rstd = rsqrtf(q * (1.f / 128.f) + 1e-6f);
;             bf16* yo = (bf16*)(ws + OFF_YB) + ((size_t)b * SEQ + j * RC + nl) * DM + h * 128;
;             const float* gn = p->in[I_RG] + (size_t)l * DM + h * 128;
; #pragma unroll
;             for (int ob = 0; ob < 8; ++ob) yo[ob * 16 + fr] = (bf16)f2bf(v[ob] * rstd * gn[ob * 16 + fr]);
;         }
;         __syncthreads();
	s_nop 1
	v_add_f32_dpp v12, v12, v12 quad_perm:[1,0,3,2] row_mask:0xf bank_mask:0xf
	v_add_f32_dpp v13, v13, v13 quad_perm:[1,0,3,2] row_mask:0xf bank_mask:0xf
	s_waitcnt lgkmcnt(0)
	s_nop 1
	v_add_f32_dpp v12, v12, v12 quad_perm:[2,3,0,1] row_mask:0xf bank_mask:0xf
	v_add_f32_dpp v13, v13, v13 quad_perm:[2,3,0,1] row_mask:0xf bank_mask:0xf
	s_waitcnt lgkmcnt(0)
	s_nop 1
	v_add_f32_dpp v12, v12, v12 row_half_mirror row_mask:0xf bank_mask:0xf
	v_add_f32_dpp v13, v13, v13 row_half_mirror row_mask:0xf bank_mask:0xf
	s_waitcnt lgkmcnt(0)
	s_nop 1
	v_add_f32_dpp v12, v12, v12 row_mirror row_mask:0xf bank_mask:0xf
	v_add_f32_dpp v13, v13, v13 row_mirror row_mask:0xf bank_mask:0xf
	s_nop 0
	v_pk_fma_f32 v[12:13], v[12:13], s[86:87], v[32:33] op_sel_hi:[1,0,0]
	s_nop 0
	v_mul_f32_e32 v16, 0x4b800000, v13
	v_cmp_gt_f32_e64 s[42:43], s19, v13
	v_cmp_gt_f32_e32 vcc, s19, v12
	s_nop 0
	v_cndmask_b32_e64 v13, v13, v16, s[42:43]
	v_rsq_f32_e32 v13, v13
	s_nop 0
	v_mul_f32_e32 v16, 0x45800000, v13
	v_cndmask_b32_e64 v13, v13, v16, s[42:43]
	v_mul_f32_e32 v14, v14, v13
	v_mul_f32_e32 v14, v54, v14
	v_cvt_pk_bf16_f32 v14, v14, s0
	ds_write_b16 v167, v14 offset:576
	v_mul_f32_e32 v14, v35, v13
	v_mul_f32_e32 v14, v53, v14
	v_cvt_pk_bf16_f32 v14, v14, s0
	ds_write_b16 v167, v14 offset:608
	v_mul_f32_e32 v14, v34, v13
	v_mul_f32_e32 v14, v52, v14
	v_cvt_pk_bf16_f32 v14, v14, s0
	ds_write_b16 v167, v14 offset:640
	v_mul_f32_e32 v14, v25, v13
	v_mul_f32_e32 v14, v51, v14
	v_cvt_pk_bf16_f32 v14, v14, s0
	ds_write_b16 v167, v14 offset:672
	v_mul_f32_e32 v14, v24, v13
	v_mul_f32_e32 v14, v50, v14
	v_cvt_pk_bf16_f32 v14, v14, s0
	v_mul_f32_e32 v16, v22, v13
	ds_write_b16 v167, v14 offset:704
	v_mul_f32_e32 v14, v27, v13
	v_mul_f32_e32 v13, v26, v13
	v_mul_f32_e32 v13, v48, v13
	v_cvt_pk_bf16_f32 v13, v13, s0
	ds_write_b16 v167, v13 offset:768
	v_mul_f32_e32 v13, 0x4b800000, v12
	v_cndmask_b32_e32 v12, v12, v13, vcc
	v_rsq_f32_e32 v12, v12
	v_mul_f32_e32 v14, v49, v14
	v_cvt_pk_bf16_f32 v14, v14, s0
	ds_write_b16 v167, v14 offset:736
	v_mul_f32_e32 v13, 0x45800000, v12
	v_cndmask_b32_e32 v14, v12, v13, vcc
	v_lshl_add_u64 v[12:13], s[34:35], 0, v[106:107]
	v_mul_f32_e32 v16, v55, v16
	v_lshlrev_b64 v[12:13], 11, v[12:13]
	v_cvt_pk_bf16_f32 v16, v16, s0
	v_lshl_add_u64 v[12:13], s[36:37], 0, v[12:13]
	ds_write_b16 v167, v16 offset:544
	v_mul_f32_e32 v16, v23, v14
	v_lshl_add_u64 v[4:5], v[12:13], 0, v[4:5]
	v_mul_f32_e32 v12, v15, v14
	v_mul_f32_e32 v11, v11, v14
	v_mul_f32_e32 v10, v10, v14
	v_mul_f32_e32 v9, v9, v14
	v_mul_f32_e32 v8, v8, v14
	v_mul_f32_e32 v7, v7, v14
	v_mul_f32_e32 v6, v6, v14
	v_mul_f32_e32 v16, v55, v16
	v_mul_f32_e32 v12, v54, v12
	v_mul_f32_e32 v11, v53, v11
	v_mul_f32_e32 v10, v52, v10
	v_mul_f32_e32 v9, v51, v9
	v_mul_f32_e32 v8, v50, v8
	v_mul_f32_e32 v7, v49, v7
	v_mul_f32_e32 v6, v48, v6
	v_cvt_pk_bf16_f32 v16, v16, s0
	v_cvt_pk_bf16_f32 v12, v12, s0
	v_cvt_pk_bf16_f32 v11, v11, s0
	v_cvt_pk_bf16_f32 v10, v10, s0
	v_cvt_pk_bf16_f32 v9, v9, s0
	v_cvt_pk_bf16_f32 v8, v8, s0
	v_cvt_pk_bf16_f32 v7, v7, s0
	v_cvt_pk_bf16_f32 v6, v6, s0
	ds_write_b16 v167, v16 offset:816
	ds_write_b16 v167, v12 offset:848
	ds_write_b16 v167, v11 offset:880
	ds_write_b16 v167, v10 offset:912
	ds_write_b16 v167, v9 offset:944
	ds_write_b16 v167, v8 offset:976
	ds_write_b16 v167, v7 offset:1008
	ds_write_b16 v167, v6 offset:1040
	v_lshrrev_b32_e32 v246, 2, v198
	v_and_b32_e32 v246, 3, v246
	v_and_b32_e32 v247, 3, v198
	v_and_b32_e32 v248, 15, v198
	v_lshlrev_b32_e32 v248, 1, v248
	v_mul_u32_u24_e32 v240, 0x110, v246
	v_lshl_add_u32 v240, v247, 6, v240
	v_sub_u32_e32 v240, v240, v248
	v_add_u32_e32 v240, v167, v240
	v_lshlrev_b32_e32 v242, 11, v246
	v_lshl_add_u32 v242, v247, 6, v242
	v_mov_b32_e32 v243, 0
	v_lshl_add_u64 v[244:245], s[34:35], 0, v[100:101]
	v_lshlrev_b64 v[244:245], 11, v[244:245]
	v_lshl_add_u64 v[244:245], s[36:37], 0, v[244:245]
	v_lshl_add_u64 v[244:245], v[244:245], 0, v[242:243]
	s_waitcnt lgkmcnt(0)
	ds_read_b128 v[224:227], v240
	ds_read_b128 v[228:231], v240 offset:16
	ds_read_b128 v[232:235], v240 offset:32
	ds_read_b128 v[236:239], v240 offset:48
	s_waitcnt lgkmcnt(3)
	global_store_dwordx4 v[244:245], v[224:227], off
	s_waitcnt lgkmcnt(2)
	global_store_dwordx4 v[244:245], v[228:231], off offset:16
	s_waitcnt lgkmcnt(1)
	global_store_dwordx4 v[244:245], v[232:235], off offset:32
	s_waitcnt lgkmcnt(0)
	global_store_dwordx4 v[244:245], v[236:239], off offset:48
	s_barrier
	s_cbranch_scc1 .LBB0_632
